# GLA backward step: 16 serialized 2-byte Y reads hoisted and issued together (on top of P6 epilogue batching)
# speedup vs baseline: 1.0068x; 1.0068x over previous
.LBB0_511:
	s_or_b64 exec, exec, s[8:9]
	ds_write_b16 v129, v74 offset:58112
	ds_write_b16_d16_hi v129, v74 offset:58256
	ds_write_b16 v129, v75 offset:58400
	ds_write_b16_d16_hi v129, v75 offset:58544
	ds_write_b16 v129, v76 offset:58688
	ds_write_b16_d16_hi v129, v76 offset:58832
	ds_write_b16 v129, v77 offset:58976
	ds_write_b16_d16_hi v129, v77 offset:59120
	ds_write_b16 v131, v70 offset:58112
	ds_write_b16_d16_hi v131, v70 offset:58256
	ds_write_b16 v133, v71 offset:58112
	ds_write_b16_d16_hi v133, v71 offset:58256
	ds_write_b16 v178, v72 offset:58112
	ds_write_b16_d16_hi v178, v72 offset:58256
	ds_write_b16 v179, v73 offset:58112
	ds_write_b16_d16_hi v179, v73 offset:58256
	s_waitcnt lgkmcnt(0)
	s_barrier
	ds_read_b128 v[2:5], v114 offset:21248
	ds_read_b128 v[6:9], v228 offset:30464
	s_waitcnt lgkmcnt(0)
	v_mfma_f32_16x16x32_bf16 v[2:5], v[2:5], v[6:9], 0
	ds_read_b128 v[6:9], v114 offset:21312
	ds_read_b128 v[10:13], v228 offset:30528
	s_lshl_b32 s15, s58, 6
	s_add_i32 s15, s15, s56
	s_waitcnt lgkmcnt(0)
	v_mfma_f32_16x16x32_bf16 v[2:5], v[6:9], v[10:13], v[2:5]
	v_mad_i64_i32 v[154:155], s[8:9], s15, v209, v[118:119]
	s_mov_b64 s[8:9], -1
	s_nop 5
	v_cvt_pk_bf16_f32 v0, v2, s0
	v_cndmask_b32_e64 v0, 0, v0, s[76:77]
	ds_write_b16 v229, v0 offset:48896
	v_cvt_pk_bf16_f32 v0, v3, s0
	v_cndmask_b32_e64 v0, 0, v0, s[78:79]
	ds_write_b16 v229, v0 offset:49040
	v_cvt_pk_bf16_f32 v0, v4, s0
	v_cndmask_b32_e64 v0, 0, v0, s[80:81]
	ds_write_b16 v229, v0 offset:49184
	v_cvt_pk_bf16_f32 v0, v5, s0
	v_cndmask_b32_e64 v0, 0, v0, s[82:83]
	ds_write_b16 v229, v0 offset:49328
	ds_read_b128 v[2:5], v114 offset:21248
	ds_read_b128 v[6:9], v230 offset:30464
	s_waitcnt lgkmcnt(0)
	v_mfma_f32_16x16x32_bf16 v[2:5], v[2:5], v[6:9], 0
	ds_read_b128 v[6:9], v114 offset:21312
	ds_read_b128 v[10:13], v230 offset:30528
	s_and_b64 vcc, exec, s[92:93]
	v_lshlrev_b32_e32 v162, 1, v126
	s_waitcnt lgkmcnt(0)
	v_mfma_f32_16x16x32_bf16 v[2:5], v[6:9], v[10:13], v[2:5]
	v_lshlrev_b32_e32 v160, 1, v128
	v_lshlrev_b32_e32 v158, 1, v130
	v_lshlrev_b32_e32 v156, 1, v132
	s_nop 4
	v_cvt_pk_bf16_f32 v0, v2, s0
	v_cndmask_b32_e64 v0, 0, v0, s[84:85]
	ds_write_b16 v229, v0 offset:48928
	v_cvt_pk_bf16_f32 v0, v3, s0
	v_cndmask_b32_e64 v0, 0, v0, s[86:87]
	ds_write_b16 v229, v0 offset:49072
	v_cvt_pk_bf16_f32 v0, v4, s0
	v_cndmask_b32_e64 v0, 0, v0, s[88:89]
	ds_write_b16 v229, v0 offset:49216
	v_cvt_pk_bf16_f32 v0, v5, s0
	v_cndmask_b32_e64 v0, 0, v0, s[90:91]
	ds_write_b16 v229, v0 offset:49360
	v_cvt_pk_bf16_f32 v0, v22, s0
	ds_write_b16 v231, v0
	v_cvt_pk_bf16_f32 v0, v23, s0
	ds_write_b16 v231, v0 offset:144
	v_cvt_pk_bf16_f32 v0, v24, s0
	ds_write_b16 v231, v0 offset:288
	v_cvt_pk_bf16_f32 v0, v25, s0
	ds_write_b16 v231, v0 offset:432
	v_cvt_pk_bf16_f32 v0, v26, s0
	ds_write_b16 v231, v0 offset:32
	v_cvt_pk_bf16_f32 v0, v27, s0
	ds_write_b16 v231, v0 offset:176
	v_cvt_pk_bf16_f32 v0, v28, s0
	ds_write_b16 v231, v0 offset:320
	v_cvt_pk_bf16_f32 v0, v29, s0
	ds_write_b16 v231, v0 offset:464
	v_cvt_pk_bf16_f32 v0, v30, s0
	ds_write_b16 v231, v0 offset:64
	v_cvt_pk_bf16_f32 v0, v31, s0
	ds_write_b16 v231, v0 offset:208
	v_cvt_pk_bf16_f32 v0, v32, s0
	ds_write_b16 v231, v0 offset:352
	v_cvt_pk_bf16_f32 v0, v33, s0
	ds_write_b16 v231, v0 offset:496
	v_cvt_pk_bf16_f32 v0, v38, s0
	ds_write_b16 v231, v0 offset:96
	v_cvt_pk_bf16_f32 v0, v39, s0
	ds_write_b16 v231, v0 offset:240
	v_cvt_pk_bf16_f32 v0, v40, s0
	ds_write_b16 v231, v0 offset:384
	v_cvt_pk_bf16_f32 v0, v41, s0
	ds_write_b16 v231, v0 offset:528
	s_waitcnt lgkmcnt(0)
	s_barrier
	ds_read_b128 v[2:5], v181 offset:48896
	ds_read_b128 v[14:17], v186 offset:58112
	ds_read_b128 v[6:9], v181 offset:21248
	ds_read_b128 v[70:73], v180
	s_waitcnt lgkmcnt(2)
	v_mfma_f32_16x16x32_bf16 v[2:5], v[2:5], v[14:17], 0
	s_waitcnt lgkmcnt(0)
	v_mfma_f32_16x16x32_bf16 v[2:5], v[6:9], v[70:73], v[2:5]
	ds_read_b128 v[6:9], v181 offset:48960
	ds_read_b128 v[74:77], v187 offset:58112
	s_waitcnt lgkmcnt(0)
	v_mfma_f32_16x16x32_bf16 v[2:5], v[6:9], v[74:77], v[2:5]
	ds_read_b128 v[6:9], v181 offset:21312
	ds_read_b128 v[78:81], v180 offset:64
	ds_read_b128 v[10:13], v181 offset:23552
	ds_read_b128 v[82:85], v181 offset:25856
	s_waitcnt lgkmcnt(2)
	v_mfma_f32_16x16x32_bf16 v[2:5], v[6:9], v[78:81], v[2:5]
	ds_read_b128 v[6:9], v181 offset:51200
	s_waitcnt lgkmcnt(0)
	v_mfma_f32_16x16x32_bf16 v[6:9], v[6:9], v[14:17], 0
	v_mfma_f32_16x16x32_bf16 v[6:9], v[10:13], v[70:73], v[6:9]
	ds_read_b128 v[10:13], v181 offset:51264
	s_waitcnt lgkmcnt(0)
	v_mfma_f32_16x16x32_bf16 v[6:9], v[10:13], v[74:77], v[6:9]
	ds_read_b128 v[10:13], v181 offset:23616
	s_waitcnt lgkmcnt(0)
	v_mfma_f32_16x16x32_bf16 v[6:9], v[10:13], v[78:81], v[6:9]
	ds_read_b128 v[10:13], v181 offset:53504
	s_waitcnt lgkmcnt(0)
	v_mfma_f32_16x16x32_bf16 v[10:13], v[10:13], v[14:17], 0
	v_mfma_f32_16x16x32_bf16 v[10:13], v[82:85], v[70:73], v[10:13]
	ds_read_b128 v[82:85], v181 offset:53568
	s_waitcnt lgkmcnt(0)
	v_mfma_f32_16x16x32_bf16 v[10:13], v[82:85], v[74:77], v[10:13]
	ds_read_b128 v[82:85], v181 offset:25920
	s_waitcnt lgkmcnt(0)
	v_mfma_f32_16x16x32_bf16 v[10:13], v[82:85], v[78:81], v[10:13]
	ds_read_b128 v[82:85], v188 offset:48896
	s_waitcnt lgkmcnt(0)
	v_mfma_f32_16x16x32_bf16 v[14:17], v[82:85], v[14:17], 0
	ds_read_b128 v[82:85], v188 offset:21248
	s_waitcnt lgkmcnt(0)
	v_mfma_f32_16x16x32_bf16 v[14:17], v[82:85], v[70:73], v[14:17]
	ds_read_b128 v[70:73], v188 offset:48960
	ds_read2_b32 v[82:83], v189 offset1:16
	s_waitcnt lgkmcnt(0)
	v_pk_mul_f32 v[24:25], v[24:25], v[82:83] op_sel_hi:[1,0]
	v_mfma_f32_16x16x32_bf16 v[14:17], v[70:73], v[74:77], v[14:17]
	ds_read_b128 v[70:73], v188 offset:21312
	v_pk_mul_f32 v[22:23], v[22:23], v[82:83] op_sel_hi:[1,0]
	v_mov_b32_e32 v0, v83
	s_waitcnt lgkmcnt(0)
	v_mfma_f32_16x16x32_bf16 v[14:17], v[70:73], v[78:81], v[14:17]
	ds_read_b128 v[70:73], v190 offset:58112
	ds_read_b128 v[74:77], v191 offset:39680
	v_pk_mul_f32 v[28:29], v[28:29], v[0:1] op_sel_hi:[1,0]
	v_pk_mul_f32 v[26:27], v[26:27], v[0:1] op_sel_hi:[1,0]
	s_waitcnt lgkmcnt(0)
	v_mfma_f32_16x16x32_bf16 v[22:25], v[70:73], v[74:77], v[22:25]
	ds_read_b128 v[74:77], v192 offset:58112
	ds_read_b128 v[78:81], v193 offset:39680
	ds_read2_b32 v[82:83], v189 offset0:32 offset1:48
	s_waitcnt lgkmcnt(0)
	v_pk_mul_f32 v[32:33], v[32:33], v[82:83] op_sel_hi:[1,0]
	v_mfma_f32_16x16x32_bf16 v[22:25], v[74:77], v[78:81], v[22:25]
	ds_read_b128 v[78:81], v194 offset:39680
	v_pk_mul_f32 v[30:31], v[30:31], v[82:83] op_sel_hi:[1,0]
	v_mov_b32_e32 v0, v83
	s_waitcnt lgkmcnt(0)
	v_mfma_f32_16x16x32_bf16 v[26:29], v[70:73], v[78:81], v[26:29]
	ds_read_b128 v[78:81], v195 offset:39680
	v_pk_mul_f32 v[40:41], v[40:41], v[0:1] op_sel_hi:[1,0]
	v_pk_mul_f32 v[38:39], v[38:39], v[0:1] op_sel_hi:[1,0]
	s_waitcnt lgkmcnt(0)
	v_mfma_f32_16x16x32_bf16 v[26:29], v[74:77], v[78:81], v[26:29]
	ds_read_b128 v[78:81], v211 offset:39680
	v_lshlrev_b32_e32 v0, 1, v124
	s_waitcnt lgkmcnt(0)
	v_mfma_f32_16x16x32_bf16 v[30:33], v[70:73], v[78:81], v[30:33]
	ds_read_b128 v[78:81], v212 offset:39680
	s_waitcnt lgkmcnt(0)
	v_mfma_f32_16x16x32_bf16 v[30:33], v[74:77], v[78:81], v[30:33]
	ds_read_b128 v[78:81], v213 offset:39680
	s_waitcnt lgkmcnt(0)
	v_mfma_f32_16x16x32_bf16 v[38:41], v[70:73], v[78:81], v[38:41]
	ds_read_b128 v[70:73], v214 offset:39680
	s_waitcnt lgkmcnt(0)
	v_mfma_f32_16x16x32_bf16 v[38:41], v[74:77], v[70:73], v[38:41]
	s_cbranch_vccnz .LBB0_513
	s_movk_i32 s8, 0x2000
	v_mov_b32_e32 v163, v1
	v_mov_b32_e32 v139, v1
	v_mov_b32_e32 v161, v1
	v_mov_b32_e32 v141, v1
	v_mov_b32_e32 v143, v1
	v_mov_b32_e32 v145, v1
	v_mov_b32_e32 v159, v1
	v_mov_b32_e32 v147, v1
	v_mov_b32_e32 v149, v1
	v_mov_b32_e32 v151, v1
	v_mov_b32_e32 v157, v1
	v_lshl_add_u64 v[70:71], v[154:155], 0, v[0:1]
	global_load_ushort v75, v[70:71], off offset:2048
	v_add_co_u32_e32 v72, vcc, 0x1000, v70
	s_nop 1
	v_addc_co_u32_e32 v73, vcc, 0, v71, vcc
	global_load_ushort v76, v[72:73], off offset:1024
	v_add_co_u32_e32 v72, vcc, s8, v70
	s_nop 1
	v_addc_co_u32_e32 v73, vcc, 0, v71, vcc
	global_load_ushort v77, v[72:73], off
	v_add_co_u32_e32 v72, vcc, 0xc000, v70
	s_nop 1
	v_addc_co_u32_e32 v73, vcc, 0, v71, vcc
	global_load_ushort v79, v[72:73], off offset:2048
	v_add_co_u32_e32 v72, vcc, 0xd000, v70
	s_nop 1
	v_addc_co_u32_e32 v73, vcc, 0, v71, vcc
	global_load_ushort v80, v[72:73], off offset:1024
	v_lshl_add_u64 v[72:73], v[154:155], 0, v[162:163]
	global_load_ushort v78, v[72:73], off offset:2048
	v_lshl_add_u64 v[72:73], v[154:155], 0, v[138:139]
	global_load_ushort v81, v[72:73], off offset:2048
	v_lshl_add_u64 v[72:73], v[154:155], 0, v[160:161]
	global_load_ushort v82, v[72:73], off offset:2048
	v_lshl_add_u64 v[72:73], v[154:155], 0, v[140:141]
	global_load_ushort v83, v[72:73], off offset:2048
	v_lshl_add_u64 v[72:73], v[154:155], 0, v[142:143]
	global_load_ushort v84, v[72:73], off offset:2048
	v_lshl_add_u64 v[72:73], v[154:155], 0, v[144:145]
	global_load_ushort v85, v[72:73], off offset:2048
	v_lshl_add_u64 v[72:73], v[154:155], 0, v[158:159]
	global_load_ushort v86, v[72:73], off offset:2048
	v_lshl_add_u64 v[72:73], v[154:155], 0, v[146:147]
	global_load_ushort v87, v[72:73], off offset:2048
	v_lshl_add_u64 v[72:73], v[154:155], 0, v[148:149]
	global_load_ushort v88, v[72:73], off offset:2048
	v_lshl_add_u64 v[72:73], v[154:155], 0, v[150:151]
	global_load_ushort v89, v[72:73], off offset:2048
	v_lshl_add_u64 v[72:73], v[154:155], 0, v[156:157]
	global_load_ushort v90, v[72:73], off offset:2048
	v_lshl_add_u64 v[70:71], v[154:155], 0, v[0:1]
	s_movk_i32 s8, 0x2000
	v_mov_b32_e32 v163, v1
	v_mov_b32_e32 v139, v1
	v_mov_b32_e32 v161, v1
	v_mov_b32_e32 v141, v1
	v_mov_b32_e32 v143, v1
	v_mov_b32_e32 v145, v1
	v_mov_b32_e32 v159, v1
	v_mov_b32_e32 v147, v1
	v_mov_b32_e32 v149, v1
	v_mov_b32_e32 v151, v1
	v_mov_b32_e32 v157, v1
	v_lshlrev_b32_e32 v164, 16, v20
	v_and_b32_e32 v165, 0xffff0000, v20
	v_mul_f32_e32 v20, 0xbfb8aa3b, v164
	v_exp_f32_e32 v20, v20
	v_lshlrev_b32_e32 v176, 16, v18
	v_and_b32_e32 v177, 0xffff0000, v18
	v_mul_f32_e32 v18, 0xbfb8aa3b, v176
	v_add_f32_e32 v20, 1.0, v20
	v_rcp_f32_e32 v170, v20
	v_mul_f32_e32 v20, 0xbfb8aa3b, v165
	v_exp_f32_e32 v20, v20
	v_exp_f32_e32 v18, v18
	v_lshlrev_b32_e32 v244, 16, v36
	v_and_b32_e32 v245, 0xffff0000, v36
	v_add_f32_e32 v20, 1.0, v20
	v_rcp_f32_e32 v171, v20
	v_add_f32_e32 v18, 1.0, v18
	v_rcp_f32_e32 v18, v18
	v_lshlrev_b32_e32 v246, 16, v35
	v_pk_mul_f32 v[164:165], v[170:171], v[164:165]
	v_lshlrev_b32_e32 v170, 16, v19
	v_and_b32_e32 v171, 0xffff0000, v19
	v_mul_f32_e32 v19, 0xbfb8aa3b, v170
	v_exp_f32_e32 v19, v19
	v_and_b32_e32 v247, 0xffff0000, v35
	v_lshlrev_b32_e32 v250, 16, v34
	v_and_b32_e32 v251, 0xffff0000, v34
	v_add_f32_e32 v19, 1.0, v19
	v_rcp_f32_e32 v174, v19
	v_mul_f32_e32 v19, 0xbfb8aa3b, v171
	v_exp_f32_e32 v19, v19
	v_add_u32_e32 v135, s15, v105
	v_add_f32_e32 v19, 1.0, v19
	v_rcp_f32_e32 v175, v19
	v_mul_f32_e32 v19, 0xbfb8aa3b, v177
	v_exp_f32_e32 v19, v19
	v_pk_mul_f32 v[170:171], v[174:175], v[170:171]
	v_add_f32_e32 v19, 1.0, v19
	v_rcp_f32_e32 v19, v19
	s_waitcnt vmcnt(0)
	v_lshlrev_b32_e32 v72, 16, v75
	v_add_f32_e32 v74, v2, v72
	v_add_co_u32_e32 v72, vcc, 0x1000, v70
	v_pk_mul_f32 v[18:19], v[18:19], v[176:177]
	s_nop 0
	v_addc_co_u32_e32 v73, vcc, 0, v71, vcc
	v_lshlrev_b32_e32 v176, 16, v37
	v_mul_f32_e32 v20, 0xbfb8aa3b, v176
	v_exp_f32_e32 v20, v20
	v_and_b32_e32 v177, 0xffff0000, v37
	v_add_f32_e32 v20, 1.0, v20
	v_rcp_f32_e32 v242, v20
	v_mul_f32_e32 v20, 0xbfb8aa3b, v177
	v_exp_f32_e32 v20, v20
	s_waitcnt vmcnt(0)
	v_lshlrev_b32_e32 v72, 16, v76
	v_add_f32_e32 v72, v3, v72
	ds_write2_b32 v232, v74, v72 offset1:132
	v_add_co_u32_e32 v72, vcc, s8, v70
	s_mov_b32 s8, 0xc000
	s_nop 0
	v_addc_co_u32_e32 v73, vcc, 0, v71, vcc
	v_add_f32_e32 v20, 1.0, v20
	v_rcp_f32_e32 v243, v20
	v_mul_f32_e32 v20, 0xbfb8aa3b, v244
	v_exp_f32_e32 v20, v20
	v_pk_mul_f32 v[176:177], v[242:243], v[176:177]
	v_add_f32_e32 v20, 1.0, v20
	v_rcp_f32_e32 v36, v20
	v_mul_f32_e32 v20, 0xbfb8aa3b, v245
	v_exp_f32_e32 v20, v20
	s_waitcnt vmcnt(0)
	v_lshlrev_b32_e32 v72, 16, v77
	v_add_f32_e32 v72, v4, v72
	ds_write_b32 v232, v72 offset:1056
	v_lshl_add_u64 v[72:73], v[154:155], 0, v[162:163]
	v_add_f32_e32 v20, 1.0, v20
	v_rcp_f32_e32 v37, v20
	v_mul_f32_e32 v20, 0xbfb8aa3b, v246
	v_exp_f32_e32 v20, v20
	v_pk_mul_f32 v[36:37], v[36:37], v[244:245]
	v_add_f32_e32 v20, 1.0, v20
	v_rcp_f32_e32 v248, v20
	v_mul_f32_e32 v20, 0xbfb8aa3b, v247
	v_exp_f32_e32 v20, v20
	s_waitcnt vmcnt(0)
	v_lshlrev_b32_e32 v72, 16, v78
	v_add_f32_e32 v72, v5, v72
	ds_write_b32 v233, v72
	v_add_co_u32_e32 v72, vcc, s8, v70
	s_mov_b32 s8, 0xd000
	s_nop 0
	v_addc_co_u32_e32 v73, vcc, 0, v71, vcc
	v_add_co_u32_e32 v70, vcc, s8, v70
	s_nop 0
	v_addc_co_u32_e32 v71, vcc, 0, v71, vcc
	v_add_u32_e32 v71, 0x2000, v232
	v_add_f32_e32 v20, 1.0, v20
	v_rcp_f32_e32 v249, v20
	v_mul_f32_e32 v20, 0xbfb8aa3b, v250
	v_exp_f32_e32 v20, v20
	s_movk_i32 s8, 0xc00
	v_pk_mul_f32 v[246:247], v[248:249], v[246:247]
	v_add_f32_e32 v20, 1.0, v20
	v_rcp_f32_e32 v34, v20
	v_mul_f32_e32 v20, 0xbfb8aa3b, v251
	v_exp_f32_e32 v20, v20
	s_waitcnt vmcnt(1)
	v_lshlrev_b32_e32 v72, 16, v79
	v_add_f32_e32 v72, v6, v72
	v_add_f32_e32 v20, 1.0, v20
	s_waitcnt vmcnt(0)
	v_lshlrev_b32_e32 v70, 16, v80
	v_add_f32_e32 v70, v7, v70
	ds_write2_b32 v71, v72, v70 offset0:64 offset1:196
	v_lshl_add_u64 v[70:71], v[154:155], 0, v[138:139]
	v_rcp_f32_e32 v35, v20
	s_waitcnt vmcnt(0)
	v_lshlrev_b32_e32 v70, 16, v81
	v_add_f32_e32 v70, v8, v70
	ds_write_b32 v232, v70 offset:9504
	v_lshl_add_u64 v[70:71], v[154:155], 0, v[160:161]
	v_pk_mul_f32 v[34:35], v[34:35], v[250:251]
	s_waitcnt vmcnt(0)
	v_lshlrev_b32_e32 v70, 16, v82
	v_add_f32_e32 v70, v9, v70
	ds_write_b32 v234, v70
	v_lshl_add_u64 v[70:71], v[154:155], 0, v[140:141]
	s_waitcnt vmcnt(0)
	v_lshlrev_b32_e32 v70, 16, v83
	v_add_f32_e32 v72, v10, v70
	v_lshl_add_u64 v[70:71], v[154:155], 0, v[142:143]
	v_add_u32_e32 v71, 0x4200, v232
	s_waitcnt vmcnt(0)
	v_lshlrev_b32_e32 v70, 16, v84
	v_add_f32_e32 v70, v11, v70
	ds_write2_b32 v71, v72, v70 offset1:132
	v_lshl_add_u64 v[70:71], v[154:155], 0, v[144:145]
	s_waitcnt vmcnt(0)
	v_lshlrev_b32_e32 v70, 16, v85
	v_add_f32_e32 v70, v12, v70
	ds_write_b32 v232, v70 offset:17952
	v_lshl_add_u64 v[70:71], v[154:155], 0, v[158:159]
	s_waitcnt vmcnt(0)
	v_lshlrev_b32_e32 v70, 16, v86
	v_add_f32_e32 v70, v13, v70
	ds_write_b32 v235, v70
	v_lshl_add_u64 v[70:71], v[154:155], 0, v[146:147]
	s_waitcnt vmcnt(0)
	v_lshlrev_b32_e32 v70, 16, v87
	v_add_f32_e32 v72, v14, v70
	v_lshl_add_u64 v[70:71], v[154:155], 0, v[148:149]
	v_add_u32_e32 v71, 0x6200, v232
	s_waitcnt vmcnt(0)
	v_lshlrev_b32_e32 v70, 16, v88
	v_add_f32_e32 v70, v15, v70
	ds_write2_b32 v71, v72, v70 offset0:64 offset1:196
	v_lshl_add_u64 v[70:71], v[154:155], 0, v[150:151]
	s_waitcnt vmcnt(0)
	v_lshlrev_b32_e32 v70, 16, v89
	v_add_f32_e32 v70, v16, v70
	ds_write_b32 v232, v70 offset:26400
	v_lshl_add_u64 v[70:71], v[154:155], 0, v[156:157]
	v_and_b32_e32 v71, 64, v197
	v_add_u32_e32 v71, 64, v71
	s_waitcnt vmcnt(0)
	v_lshlrev_b32_e32 v70, 16, v90
	v_add_f32_e32 v70, v17, v70
	ds_write_b32 v236, v70
	v_xor_b32_e32 v70, 1, v197
	v_cmp_lt_i32_e32 vcc, v70, v71
	s_waitcnt lgkmcnt(0)
	s_barrier
	v_cndmask_b32_e32 v70, v197, v70, vcc
	v_lshlrev_b32_e32 v137, 2, v70
	v_xor_b32_e32 v70, 2, v197
	v_cmp_lt_i32_e32 vcc, v70, v71
	s_nop 1
	v_cndmask_b32_e32 v70, v197, v70, vcc
	v_lshlrev_b32_e32 v139, 2, v70
	v_xor_b32_e32 v70, 4, v197
	v_cmp_lt_i32_e32 vcc, v70, v71
	s_nop 1
	v_cndmask_b32_e32 v70, v197, v70, vcc
	v_lshlrev_b32_e32 v141, 2, v70
	ds_read_b128 v[82:85], v237
	ds_read_b128 v[74:77], v237 offset:16
	ds_read_b128 v[78:81], v237 offset:32
	ds_read_b128 v[70:73], v237 offset:48
	global_load_dwordx4 v[86:89], v[116:117], off offset:48
	global_load_dwordx4 v[90:93], v[116:117], off offset:32
	global_load_dwordx4 v[94:97], v[116:117], off offset:16
	global_load_dwordx4 v[98:101], v[116:117], off
	s_waitcnt lgkmcnt(3)
	v_pk_mul_f32 v[248:249], v[82:83], v[82:83]
	v_pk_mul_f32 v[244:245], v[84:85], v[84:85]
	v_add_f32_e32 v20, v248, v249
	v_add_f32_e32 v20, v20, v244
	s_waitcnt lgkmcnt(2)
	v_pk_mul_f32 v[242:243], v[74:75], v[74:75]
	v_add_f32_e32 v20, v20, v245
	v_add_f32_e32 v20, v20, v242
	v_pk_mul_f32 v[240:241], v[76:77], v[76:77]
	v_add_f32_e32 v20, v20, v243
	v_add_f32_e32 v20, v20, v240
	s_waitcnt lgkmcnt(1)
	v_pk_mul_f32 v[174:175], v[78:79], v[78:79]
	v_add_f32_e32 v20, v20, v241
	v_add_f32_e32 v20, v20, v174
	v_pk_mul_f32 v[172:173], v[80:81], v[80:81]
	v_add_f32_e32 v20, v20, v175
	v_add_f32_e32 v20, v20, v172
	s_waitcnt lgkmcnt(0)
	v_pk_mul_f32 v[168:169], v[70:71], v[70:71]
	v_add_f32_e32 v20, v20, v173
	v_add_f32_e32 v20, v20, v168
	v_pk_mul_f32 v[166:167], v[72:73], v[72:73]
	v_add_f32_e32 v20, v20, v169
	v_add_f32_e32 v20, v20, v166
	v_add_f32_e32 v20, v20, v167
	ds_bpermute_b32 v137, v137, v20
	s_waitcnt lgkmcnt(0)
	v_add_f32_e32 v20, v20, v137
	ds_bpermute_b32 v137, v139, v20
	s_waitcnt lgkmcnt(0)
	v_add_f32_e32 v20, v20, v137
	ds_bpermute_b32 v137, v141, v20
	s_waitcnt lgkmcnt(0)
	v_add_f32_e32 v20, v20, v137
	v_fmamk_f32 v20, v20, 0x3c000000, v198
	v_rsq_f32_e32 v166, v20
	s_nop 0
	v_pk_mul_f32 v[74:75], v[74:75], v[166:167] op_sel_hi:[1,0]
	v_pk_mul_f32 v[70:71], v[70:71], v[166:167] op_sel_hi:[1,0]
	v_pk_mul_f32 v[82:83], v[82:83], v[166:167] op_sel_hi:[1,0]
	v_pk_mul_f32 v[72:73], v[72:73], v[166:167] op_sel_hi:[1,0]
	s_waitcnt vmcnt(3)
	v_pk_mul_f32 v[70:71], v[70:71], v[86:87]
	s_nop 0
	v_pk_mul_f32 v[70:71], v[164:165], v[70:71]
	s_waitcnt vmcnt(1)
	v_pk_mul_f32 v[74:75], v[94:95], v[74:75]
	v_cvt_pk_bf16_f32 v20, v70, v71
	v_pk_mul_f32 v[36:37], v[36:37], v[74:75]
	v_pk_mul_f32 v[74:75], v[76:77], v[166:167] op_sel_hi:[1,0]
	v_lshlrev_b32_e32 v70, 16, v21
	v_pk_mul_f32 v[74:75], v[74:75], v[96:97]
	v_and_b32_e32 v71, 0xffff0000, v21
	v_pk_mul_f32 v[74:75], v[176:177], v[74:75]
	v_mul_f32_e32 v21, 0xbfb8aa3b, v70
	v_cvt_pk_bf16_f32 v36, v36, v37
	v_cvt_pk_bf16_f32 v37, v74, v75
	v_pk_mul_f32 v[74:75], v[78:79], v[166:167] op_sel_hi:[1,0]
	v_exp_f32_e32 v21, v21
	v_pk_mul_f32 v[74:75], v[74:75], v[90:91]
	s_waitcnt vmcnt(0)
	v_pk_mul_f32 v[82:83], v[98:99], v[82:83]
	v_pk_mul_f32 v[18:19], v[18:19], v[74:75]
	v_pk_mul_f32 v[74:75], v[80:81], v[166:167] op_sel_hi:[1,0]
	v_add_f32_e32 v21, 1.0, v21
	v_pk_mul_f32 v[74:75], v[74:75], v[92:93]
	v_cvt_pk_bf16_f32 v18, v18, v19
	v_pk_mul_f32 v[74:75], v[170:171], v[74:75]
	v_pk_mul_f32 v[34:35], v[34:35], v[82:83]
	v_cvt_pk_bf16_f32 v19, v74, v75
	v_rcp_f32_e32 v74, v21
	v_mul_f32_e32 v21, 0xbfb8aa3b, v71
	v_exp_f32_e32 v21, v21
	v_pk_mul_f32 v[82:83], v[84:85], v[166:167] op_sel_hi:[1,0]
	v_pk_mul_f32 v[72:73], v[72:73], v[88:89]
	v_pk_mul_f32 v[82:83], v[100:101], v[82:83]
	v_add_f32_e32 v21, 1.0, v21
	v_rcp_f32_e32 v75, v21
	v_pk_mul_f32 v[82:83], v[246:247], v[82:83]
	v_cvt_pk_bf16_f32 v34, v34, v35
	v_cvt_pk_bf16_f32 v35, v82, v83
	v_pk_mul_f32 v[70:71], v[74:75], v[70:71]
	s_nop 0
	v_pk_mul_f32 v[70:71], v[70:71], v[72:73]
	s_nop 0
	v_cvt_pk_bf16_f32 v21, v70, v71
	v_mad_i64_i32 v[70:71], s[8:9], v135, s8, v[120:121]
	s_mov_b64 s[8:9], 0
	global_store_dwordx4 v[70:71], v[34:37], off offset:2048
	global_store_dwordx4 v[70:71], v[18:21], off offset:2064
